# conv token groups rebalanced 3/2/1 per wave; conv 16-lane reductions by DPP
# speedup vs baseline: 1.1040x; 1.0043x over previous
; #define REP(k) for (int rep_ = 0; rep_ < (((REPMASK) >> (k)) & 1) + 1; ++rep_)
; __global__ void __launch_bounds__(NTHREADS) mega_fwd(P p) {
;     ...
;                 PH();
;                 if (ngw == 2048) {
;                     const int vcu = ((int)blockIdx.x % 8) * (G / 8) + (int)blockIdx.x / 8, gwv = vcu * 8 + wave;
;                     if (RUN(6)) REP(6) {
;                         if (gwv >= 1024) { for (int k = 0; k < 4; ++k) dn_conv_token4(q, ((gwv - 1024) * 4 + k) * 4, lane); }
;                         else if (gwv < 512) dn_conv_token4(q, (4096 + gwv) * 4, lane);
;                     }
;                 } else if (RUN(6)) REP(6) for (int m = gw * 4; m < MALL; m += ngw * 4) dn_conv_token4(q, m, lane);
.LBB0_453:
	s_andn2_b64 vcc, exec, s[6:7]
	s_cbranch_vccnz .LBB0_521
	v_readlane_b32 s6, v253, 61
	s_add_i32 s12, s6, s62
	s_lshl_b32 s13, s12, 2
	s_waitcnt lgkmcnt(0)
	s_add_u32 s16, s2, 0xfd00000
	s_addc_u32 s17, s3, 0
	s_add_u32 s18, s2, 0xff00000
	v_and_b32_e32 v109, 15, v144
	s_addc_u32 s19, s3, 0
	v_lshlrev_b32_e32 v0, 4, v110
	v_lshlrev_b32_e32 v2, 2, v109
	v_mov_b32_e32 v3, v1
	s_cmpk_lt_i32 s12, 0x400
	v_lshl_add_u64 v[74:75], s[2:3], 0, v[0:1]
	v_lshrrev_b32_e32 v108, 4, v110
	v_cmp_lt_u32_e64 s[6:7], 7, v109
	v_lshl_add_u64 v[76:77], s[8:9], 0, v[2:3]
	v_lshl_add_u64 v[78:79], s[74:75], 0, v[2:3]
	s_mov_b64 s[8:9], -1
	s_cmpk_lt_i32 s12, 0x400
	s_cbranch_scc1 .Lcv_lo
	s_add_i32 s98, s12, 0xfffffc00
	s_mul_i32 s98, s98, 3
	s_mov_b32 s99, 3
	s_branch .LBB0_488
.Lcv_lo:
	s_cmpk_lt_i32 s12, 0x200
	s_cbranch_scc0 .Lcv_mid
	s_lshl_b32 s98, s12, 1
	s_add_i32 s98, s98, 0xc00
	s_mov_b32 s99, 2
	s_branch .LBB0_488
.Lcv_mid:
	s_add_i32 s98, s12, 0xe00
	s_mov_b32 s99, 1
	s_branch .LBB0_488

; #define REP(k) for (int rep_ = 0; rep_ < (((REPMASK) >> (k)) & 1) + 1; ++rep_)
; __device__ __forceinline__ void dn_conv_token4(const P& p, int m0, int lane) {
;     ...
;     {
;         const int m = m0 + (lane >> 4), idx = lane & 15;
;         const float a = ((const float*)(p.ws + WS_AB))[(size_t)m * 16 + idx];
;         float r;
;         if (idx < 8) { const float xx = a + p.dt_bias[idx]; const float sp = fmaxf(xx, 0.f) + log1pf(__expf(-fabsf(xx))); r = -__expf(p.a_log[idx]) * sp; }
;         else r = 1.f / (1.f + __expf(-a));
;         ((float*)(p.ws + WS_GB))[(size_t)m * 16 + idx] = r;
; __global__ void __launch_bounds__(NTHREADS) mega_fwd(P p) {
;     ...
;                 if (ngw == 2048) {
;                     const int vcu = ((int)blockIdx.x % 8) * (G / 8) + (int)blockIdx.x / 8, gwv = vcu * 8 + wave;
;                     if (RUN(6)) REP(6) {
;                         if (gwv >= 1024) { for (int k = 0; k < 4; ++k) dn_conv_token4(q, ((gwv - 1024) * 4 + k) * 4, lane); }
;                         else if (gwv < 512) dn_conv_token4(q, (4096 + gwv) * 4, lane);
;                     }
;                 } else if (RUN(6)) REP(6) for (int m = gw * 4; m < MALL; m += ngw * 4) dn_conv_token4(q, m, lane);
.LBB0_488:
	s_andn2_b64 vcc, exec, s[8:9]
	s_cbranch_vccnz .LBB0_521
	s_mov_b32 s88, s98
	s_add_u32 s89, s2, 0xb500000
	s_addc_u32 s90, s3, 0
	s_lshl_b32 s8, s98, 2
	s_add_i32 s8, s8, 0x4000
	s_add_i32 s9, s8, 0xffffc000
	s_add_i32 s91, s8, 0xffffbffe
	s_add_i32 s92, s8, 0xffffbfff
	s_mul_hi_i32 s10, s9, 0xc00
	s_mulk_i32 s9, 0xc00
	v_lshlrev_b32_e32 v2, 5, v110
	v_mov_b32_e32 v3, v1
	s_add_u32 s2, s2, s9
	v_lshl_add_u64 v[80:81], s[72:73], 0, v[2:3]
	s_addc_u32 s3, s3, s10
	s_add_i32 s93, s8, 0xffffc005
	s_add_i32 s94, s8, 0xffffc004
	s_mov_b32 s95, 0
	s_branch .LBB0_491
.LBB0_490:
	s_or_b64 exec, exec, s[8:9]
	s_add_i32 s95, s95, 1
	s_add_i32 s91, s91, 4
	s_add_i32 s92, s92, 4
	s_add_u32 s2, s2, 0x3000
	s_addc_u32 s3, s3, 0
	s_add_i32 s93, s93, 4
	s_add_i32 s94, s94, 4
	v_lshl_add_u64 v[2:3], v[2:3], 2, s[18:19]
	s_cmp_eq_u32 s95, s99
	global_store_dword v[2:3], v4, off
	s_cbranch_scc1 .LBB0_521

; __device__ __forceinline__ float siluf(float v) { return v * __builtin_amdgcn_rcpf(1.f + __expf(-v)); }
; __device__ __forceinline__ void dn_conv_token4(const P& p, int m0, int lane) {
;     ...
;         for (int t = 0; t < 4; ++t) {
;             float acc[8];
; #pragma unroll
;             for (int i = 0; i < 8; ++i) acc[i] = 0.f;
; #pragma unroll
;             for (int j = 0; j < 5; ++j) { const u32x4 xv = xr[t + j];
;                 acc[0] += bflo(xv.x) * w[j][0][0]; acc[1] += bfhi(xv.x) * w[j][0][1]; acc[2] += bflo(xv.y) * w[j][0][2]; acc[3] += bfhi(xv.y) * w[j][0][3];
;                 acc[4] += bflo(xv.z) * w[j][1][0]; acc[5] += bfhi(xv.z) * w[j][1][1]; acc[6] += bflo(xv.w) * w[j][1][2]; acc[7] += bfhi(xv.w) * w[j][1][3]; }
;             float ss = 0.f;
; #pragma unroll
;             for (int i = 0; i < 8; ++i) { acc[i] = siluf(acc[i]); ss += acc[i] * acc[i]; }
;             if (cgp < 2) {
;                 ss += __shfl_xor(ss, 1); ss += __shfl_xor(ss, 2); ss += __shfl_xor(ss, 4); ss += __shfl_xor(ss, 8);
;                 const float rn = 1.0f / sqrtf(ss + EPS);
; #pragma unroll
;                 for (int i = 0; i < 8; ++i) acc[i] *= rn;
;             }
.LBB0_509:
	s_waitcnt vmcnt(0)
	v_lshlrev_b32_e32 v94, 16, v66
	v_and_b32_e32 v95, 0xffff0000, v66
	v_lshlrev_b32_e32 v92, 16, v67
	v_and_b32_e32 v93, 0xffff0000, v67
	v_and_b32_e32 v91, 0xffff0000, v68
	v_lshlrev_b32_e32 v90, 16, v68
	v_and_b32_e32 v89, 0xffff0000, v69
	v_lshlrev_b32_e32 v88, 16, v69
	v_mov_b32_e32 v82, v9
	v_lshlrev_b32_e32 v84, 16, v62
	v_and_b32_e32 v85, 0xffff0000, v62
	v_lshlrev_b32_e32 v66, 16, v63
	v_and_b32_e32 v67, 0xffff0000, v63
	v_lshlrev_b32_e32 v68, 16, v71
	v_and_b32_e32 v69, 0xffff0000, v71
	v_and_b32_e32 v63, 0xffff0000, v72
	v_lshlrev_b32_e32 v62, 16, v72
	v_lshlrev_b32_e32 v9, 16, v73
	v_and_b32_e32 v71, 0xffff0000, v73
	v_lshlrev_b32_e32 v72, 16, v54
	v_and_b32_e32 v73, 0xffff0000, v54
	v_lshlrev_b32_e32 v102, 16, v58
	v_and_b32_e32 v103, 0xffff0000, v58
	v_pk_fma_f32 v[72:73], v[14:15], v[72:73], 0 op_sel_hi:[1,1,0]
	v_lshlrev_b32_e32 v86, 16, v70
	v_pk_fma_f32 v[72:73], v[22:23], v[102:103], v[72:73]
	v_and_b32_e32 v87, 0xffff0000, v70
	v_pk_fma_f32 v[72:73], v[30:31], v[94:95], v[72:73]
	v_mov_b32_e32 v83, v13
	v_pk_fma_f32 v[72:73], v[34:35], v[84:85], v[72:73]
	v_lshlrev_b32_e32 v54, 16, v55
	v_pk_fma_f32 v[72:73], v[38:39], v[86:87], v[72:73]
	v_and_b32_e32 v55, 0xffff0000, v55
	v_mul_f32_e32 v13, 0xbfb8aa3b, v72
	v_exp_f32_e32 v13, v13
	v_lshlrev_b32_e32 v100, 16, v59
	v_and_b32_e32 v101, 0xffff0000, v59
	v_pk_fma_f32 v[54:55], v[16:17], v[54:55], 0 op_sel_hi:[1,1,0]
	v_add_f32_e32 v13, 1.0, v13
	v_rcp_f32_e32 v104, v13
	v_mul_f32_e32 v13, 0xbfb8aa3b, v73
	v_exp_f32_e32 v13, v13
	v_pk_fma_f32 v[54:55], v[24:25], v[100:101], v[54:55]
	v_and_b32_e32 v99, 0xffff0000, v60
	v_pk_fma_f32 v[54:55], v[32:33], v[92:93], v[54:55]
	v_add_f32_e32 v13, 1.0, v13
	v_pk_fma_f32 v[54:55], v[36:37], v[66:67], v[54:55]
	v_rcp_f32_e32 v105, v13
	v_pk_fma_f32 v[54:55], v[40:41], v[68:69], v[54:55]
	v_lshlrev_b32_e32 v98, 16, v60
	v_mul_f32_e32 v13, 0xbfb8aa3b, v54
	v_exp_f32_e32 v13, v13
	v_pk_mul_f32 v[72:73], v[72:73], v[104:105]
	v_and_b32_e32 v97, 0xffff0000, v61
	v_lshlrev_b32_e32 v96, 16, v61
	v_add_f32_e32 v13, 1.0, v13
	v_rcp_f32_e32 v104, v13
	v_mul_f32_e32 v13, 0xbfb8aa3b, v55
	v_exp_f32_e32 v13, v13
	v_and_b32_e32 v61, 0xffff0000, v64
	v_lshlrev_b32_e32 v60, 16, v64
	v_mov_b32_e32 v58, v97
	v_add_f32_e32 v13, 1.0, v13
	v_rcp_f32_e32 v105, v13
	v_mov_b32_e32 v59, v89
	v_pk_mul_f32 v[114:115], v[82:83], v[58:59]
	v_and_b32_e32 v59, 0xffff0000, v65
	v_pk_mul_f32 v[104:105], v[54:55], v[104:105]
	v_and_b32_e32 v55, 0xffff0000, v56
	v_lshlrev_b32_e32 v54, 16, v56
	v_pk_fma_f32 v[54:55], v[2:3], v[54:55], 0 op_sel_hi:[1,1,0]
	v_mul_f32_e32 v110, v8, v96
	v_pk_fma_f32 v[54:55], v[6:7], v[98:99], v[54:55]
	v_lshlrev_b32_e32 v58, 16, v65
	v_pk_fma_f32 v[54:55], v[10:11], v[90:91], v[54:55]
	v_mov_b32_e32 v64, v21
	v_pk_fma_f32 v[54:55], v[18:19], v[60:61], v[54:55]
	v_mov_b32_e32 v65, v29
	v_pk_fma_f32 v[54:55], v[26:27], v[62:63], v[54:55]
	v_mov_b32_e32 v70, v59
	v_mul_f32_e32 v13, 0xbfb8aa3b, v54
	v_exp_f32_e32 v13, v13
	v_mov_b32_e32 v111, v114
	v_mul_f32_e32 v112, v12, v88
	v_pk_mul_f32 v[120:121], v[64:65], v[70:71]
	v_add_f32_e32 v13, 1.0, v13
	v_rcp_f32_e32 v106, v13
	v_mul_f32_e32 v13, 0xbfb8aa3b, v55
	v_exp_f32_e32 v13, v13
	v_mov_b32_e32 v113, v115
	v_mul_f32_e32 v116, v20, v58
	v_mov_b32_e32 v117, v120
	v_add_f32_e32 v13, 1.0, v13
	v_rcp_f32_e32 v107, v13
	v_mul_f32_e32 v118, v28, v9
	v_mov_b32_e32 v119, v121
	s_cmpk_lg_i32 s84, 0x1000
	v_pk_mul_f32 v[106:107], v[54:55], v[106:107]
	v_and_b32_e32 v55, 0xffff0000, v57
	v_lshlrev_b32_e32 v54, 16, v57
	v_pk_fma_f32 v[54:55], v[4:5], v[54:55], 0 op_sel_hi:[1,1,0]
	s_cselect_b64 s[10:11], -1, 0
	v_pk_add_f32 v[54:55], v[54:55], v[110:111]
	s_cmpk_eq_i32 s84, 0x1000
	v_pk_add_f32 v[54:55], v[54:55], v[112:113]
	s_nop 0
	v_pk_add_f32 v[54:55], v[54:55], v[116:117]
	s_nop 0
	v_pk_add_f32 v[54:55], v[54:55], v[118:119]
	s_nop 0
	v_mul_f32_e32 v13, 0xbfb8aa3b, v54
	v_exp_f32_e32 v13, v13
	s_nop 0
	v_add_f32_e32 v13, 1.0, v13
	v_rcp_f32_e32 v56, v13
	v_mul_f32_e32 v13, 0xbfb8aa3b, v55
	v_exp_f32_e32 v13, v13
	s_nop 0
	v_add_f32_e32 v13, 1.0, v13
	v_rcp_f32_e32 v57, v13
	s_nop 0
	v_pk_mul_f32 v[56:57], v[54:55], v[56:57]
	s_cbranch_scc1 .LBB0_511
	v_pk_mul_f32 v[54:55], v[72:73], v[72:73]
	v_pk_mul_f32 v[110:111], v[104:105], v[104:105]
	v_add_f32_e32 v13, v54, v55
	v_add_f32_e32 v13, v110, v13
	v_pk_mul_f32 v[112:113], v[106:107], v[106:107]
	v_add_f32_e32 v13, v111, v13
	v_add_f32_e32 v13, v112, v13
	v_pk_mul_f32 v[114:115], v[56:57], v[56:57]
	v_add_f32_e32 v13, v113, v13
	v_cmp_lt_i32_e32 vcc, v192, v186
	v_add_f32_e32 v13, v114, v13
	v_add_f32_e32 v13, v115, v13
	s_nop 1
	v_add_f32_dpp v13, v13, v13 quad_perm:[1,0,3,2] row_mask:0xf bank_mask:0xf
	s_nop 1
	v_add_f32_dpp v13, v13, v13 quad_perm:[2,3,0,1] row_mask:0xf bank_mask:0xf
	s_nop 1
	v_add_f32_dpp v13, v13, v13 row_half_mirror row_mask:0xf bank_mask:0xf
	s_nop 1
	v_add_f32_dpp v13, v13, v13 row_mirror row_mask:0xf bank_mask:0xf
	s_nop 0
	v_add_f32_e32 v13, 0x358637bd, v13
	v_mul_f32_e32 v21, 0x4f800000, v13
	v_cmp_gt_f32_e32 vcc, s53, v13
	s_nop 1
	v_cndmask_b32_e32 v13, v13, v21, vcc
	v_sqrt_f32_e32 v21, v13
	s_nop 0
	v_add_u32_e32 v29, -1, v21
	v_add_u32_e32 v54, 1, v21
	v_fma_f32 v55, -v29, v21, v13
	v_fma_f32 v110, -v54, v21, v13
	v_cmp_ge_f32_e64 s[8:9], 0, v55
	s_nop 1
	v_cndmask_b32_e64 v21, v21, v29, s[8:9]
	v_cmp_lt_f32_e64 s[8:9], 0, v110
	s_nop 1
	v_cndmask_b32_e64 v21, v21, v54, s[8:9]
	v_mul_f32_e32 v29, 0x37800000, v21
	v_cndmask_b32_e32 v21, v21, v29, vcc
	v_cmp_class_f32_e32 vcc, v13, v195
	s_nop 1
	v_cndmask_b32_e32 v13, v21, v13, vcc
	v_div_scale_f32 v21, s[8:9], v13, v13, 1.0
	v_rcp_f32_e32 v29, v21
	s_nop 0
	v_fma_f32 v54, -v21, v29, 1.0
	v_fmac_f32_e32 v29, v54, v29
	v_div_scale_f32 v54, vcc, 1.0, v13, 1.0
	v_mul_f32_e32 v55, v54, v29
	v_fma_f32 v110, -v21, v55, v54
	v_fmac_f32_e32 v55, v110, v29
	v_fma_f32 v21, -v21, v55, v54
	v_div_fmas_f32 v21, v21, v29, v55
	v_div_fixup_f32 v54, v21, v13, 1.0
	v_pk_mul_f32 v[56:57], v[56:57], v[54:55] op_sel_hi:[1,0]
	v_pk_mul_f32 v[106:107], v[106:107], v[54:55] op_sel_hi:[1,0]
	v_pk_mul_f32 v[104:105], v[104:105], v[54:55] op_sel_hi:[1,0]
	v_pk_mul_f32 v[72:73], v[72:73], v[54:55] op_sel_hi:[1,0]
; __device__ __forceinline__ unsigned pk2(float lo, float hi) { unsigned r; asm("v_cvt_pk_bf16_f32 %0, %1, %2" : "=v"(r) : "v"(lo), "v"(hi)); return r; }
; __device__ __forceinline__ float siluf(float v) { return v * __builtin_amdgcn_rcpf(1.f + __expf(-v)); }
; __device__ __forceinline__ void dn_conv_token4(const P& p, int m0, int lane) {
;     ...
;         bf16_t* dbase = (bf16_t*)(p.ws + (cgp == 0 ? WS_QN : (cgp == 1 ? WS_KN : WS_VV))) + lane * 8;
; #pragma unroll
;         for (int t = 0; t < 4; ++t) {
;             float acc[8];
; #pragma unroll
;             for (int i = 0; i < 8; ++i) acc[i] = 0.f;
; #pragma unroll
;             for (int j = 0; j < 5; ++j) { const u32x4 xv = xr[t + j];
;                 acc[0] += bflo(xv.x) * w[j][0][0]; acc[1] += bfhi(xv.x) * w[j][0][1]; acc[2] += bflo(xv.y) * w[j][0][2]; acc[3] += bfhi(xv.y) * w[j][0][3];
;                 acc[4] += bflo(xv.z) * w[j][1][0]; acc[5] += bfhi(xv.z) * w[j][1][1]; acc[6] += bflo(xv.w) * w[j][1][2]; acc[7] += bfhi(xv.w) * w[j][1][3]; }
;             float ss = 0.f;
; #pragma unroll
;             for (int i = 0; i < 8; ++i) { acc[i] = siluf(acc[i]); ss += acc[i] * acc[i]; }
;             if (cgp < 2) {
;                 ss += __shfl_xor(ss, 1); ss += __shfl_xor(ss, 2); ss += __shfl_xor(ss, 4); ss += __shfl_xor(ss, 8);
;                 const float rn = 1.0f / sqrtf(ss + EPS);
; #pragma unroll
;                 for (int i = 0; i < 8; ++i) acc[i] *= rn;
;             }
;             u32x4 o; o.x = pk2(acc[0], acc[1]); o.y = pk2(acc[2], acc[3]); o.z = pk2(acc[4], acc[5]); o.w = pk2(acc[6], acc[7]);
;             *(u32x4*)(dbase + (size_t)(m0 + t) * 512) = o;
.LBB0_511:
	v_pk_fma_f32 v[102:103], v[14:15], v[102:103], 0 op_sel_hi:[1,1,0]
	v_cvt_pk_bf16_f32 v110, v72, v73
	v_lshlrev_b32_e32 v72, 16, v50
	v_pk_fma_f32 v[102:103], v[22:23], v[94:95], v[102:103]
	v_and_b32_e32 v73, 0xffff0000, v50
	v_pk_fma_f32 v[102:103], v[30:31], v[84:85], v[102:103]
	s_cmpk_eq_i32 s84, 0x800
	v_pk_fma_f32 v[102:103], v[34:35], v[86:87], v[102:103]
	s_mov_b32 s1, 0x11300000
	v_pk_fma_f32 v[102:103], v[38:39], v[72:73], v[102:103]
	s_cselect_b32 s8, s1, 0x12500000
	v_mul_f32_e32 v21, 0xbfb8aa3b, v102
	v_exp_f32_e32 v21, v21
	s_cmp_lg_u32 s84, 0
	s_cselect_b32 s64, s8, 0x10100000
	v_lshl_add_u64 v[54:55], v[74:75], 0, s[64:65]
	v_add_f32_e32 v21, 1.0, v21
	v_rcp_f32_e32 v118, v21
	v_mul_f32_e32 v21, 0xbfb8aa3b, v103
	v_exp_f32_e32 v21, v21
	v_pk_fma_f32 v[100:101], v[16:17], v[100:101], 0 op_sel_hi:[1,1,0]
	v_cvt_pk_bf16_f32 v113, v56, v57
	v_lshl_add_u64 v[56:57], v[54:55], 0, s[48:49]
	v_pk_fma_f32 v[100:101], v[24:25], v[92:93], v[100:101]
	v_cvt_pk_bf16_f32 v111, v104, v105
	v_cvt_pk_bf16_f32 v112, v106, v107
	global_store_dwordx4 v[56:57], v[110:113], off
	v_mov_b32_e32 v56, v89
	v_mov_b32_e32 v57, v59
	v_pk_fma_f32 v[100:101], v[32:33], v[66:67], v[100:101]
	v_pk_mul_f32 v[110:111], v[82:83], v[56:57]
	v_lshlrev_b32_e32 v56, 16, v51
	v_and_b32_e32 v57, 0xffff0000, v51
	v_pk_fma_f32 v[100:101], v[36:37], v[68:69], v[100:101]
	v_add_f32_e32 v21, 1.0, v21
	v_pk_fma_f32 v[100:101], v[40:41], v[56:57], v[100:101]
	v_rcp_f32_e32 v119, v21
	v_mul_f32_e32 v21, 0xbfb8aa3b, v100
	v_exp_f32_e32 v21, v21
	v_pk_fma_f32 v[98:99], v[2:3], v[98:99], 0 op_sel_hi:[1,1,0]
	v_pk_mul_f32 v[102:103], v[102:103], v[118:119]
	v_pk_fma_f32 v[98:99], v[6:7], v[90:91], v[98:99]
	v_add_f32_e32 v21, 1.0, v21
	v_rcp_f32_e32 v118, v21
	v_mul_f32_e32 v21, 0xbfb8aa3b, v101
	v_exp_f32_e32 v21, v21
	v_pk_fma_f32 v[98:99], v[10:11], v[60:61], v[98:99]
	v_and_b32_e32 v51, 0xffff0000, v52
	v_lshlrev_b32_e32 v50, 16, v52
	v_pk_fma_f32 v[98:99], v[18:19], v[62:63], v[98:99]
	v_add_f32_e32 v21, 1.0, v21
	v_pk_fma_f32 v[98:99], v[26:27], v[50:51], v[98:99]
	v_rcp_f32_e32 v119, v21
	v_mul_f32_e32 v21, 0xbfb8aa3b, v98
	v_exp_f32_e32 v21, v21
	v_mul_f32_e32 v104, v8, v88
	v_pk_mul_f32 v[100:101], v[100:101], v[118:119]
	v_lshlrev_b32_e32 v13, 16, v53
	v_add_f32_e32 v21, 1.0, v21
	v_rcp_f32_e32 v118, v21
	v_mul_f32_e32 v21, 0xbfb8aa3b, v99
	v_and_b32_e32 v53, 0xffff0000, v53
	v_mov_b32_e32 v52, v71
	v_exp_f32_e32 v21, v21
	v_pk_fma_f32 v[96:97], v[4:5], v[96:97], 0 op_sel_hi:[1,1,0]
	v_mov_b32_e32 v105, v110
	v_mul_f32_e32 v106, v12, v58
	v_pk_mul_f32 v[116:117], v[64:65], v[52:53]
	v_pk_add_f32 v[96:97], v[96:97], v[104:105]
	v_mov_b32_e32 v107, v111
	v_mul_f32_e32 v112, v20, v9
	v_pk_add_f32 v[96:97], v[96:97], v[106:107]
	v_mov_b32_e32 v113, v116
	v_mul_f32_e32 v114, v28, v13
	v_pk_add_f32 v[96:97], v[96:97], v[112:113]
	v_mov_b32_e32 v115, v117
	v_add_f32_e32 v21, 1.0, v21
	v_pk_add_f32 v[96:97], v[96:97], v[114:115]
	v_rcp_f32_e32 v119, v21
	v_mul_f32_e32 v21, 0xbfb8aa3b, v96
	v_exp_f32_e32 v21, v21
	s_andn2_b64 vcc, exec, s[10:11]
	v_pk_mul_f32 v[98:99], v[98:99], v[118:119]
	v_add_f32_e32 v21, 1.0, v21
	v_rcp_f32_e32 v104, v21
	v_mul_f32_e32 v21, 0xbfb8aa3b, v97
	v_exp_f32_e32 v21, v21
	s_nop 0
	v_add_f32_e32 v21, 1.0, v21
	v_rcp_f32_e32 v105, v21
	v_cndmask_b32_e64 v21, 0, 1, s[10:11]
	v_cmp_ne_u32_e64 s[8:9], 1, v21
	v_pk_mul_f32 v[96:97], v[96:97], v[104:105]
	s_cbranch_vccnz .LBB0_513
	v_pk_mul_f32 v[104:105], v[102:103], v[102:103]
	v_pk_mul_f32 v[106:107], v[100:101], v[100:101]
	v_add_f32_e32 v21, v104, v105
	v_add_f32_e32 v21, v106, v21
	v_pk_mul_f32 v[110:111], v[98:99], v[98:99]
	v_add_f32_e32 v21, v107, v21
	v_add_f32_e32 v21, v110, v21
	v_pk_mul_f32 v[112:113], v[96:97], v[96:97]
	v_add_f32_e32 v21, v111, v21
	v_cmp_lt_i32_e32 vcc, v192, v186
	v_add_f32_e32 v21, v112, v21
	v_add_f32_e32 v21, v113, v21
	s_nop 1
	v_add_f32_dpp v21, v21, v21 quad_perm:[1,0,3,2] row_mask:0xf bank_mask:0xf
	s_nop 1
	v_add_f32_dpp v21, v21, v21 quad_perm:[2,3,0,1] row_mask:0xf bank_mask:0xf
	s_nop 1
	v_add_f32_dpp v21, v21, v21 row_half_mirror row_mask:0xf bank_mask:0xf
	s_nop 1
	v_add_f32_dpp v21, v21, v21 row_mirror row_mask:0xf bank_mask:0xf
	s_nop 0
	v_add_f32_e32 v21, 0x358637bd, v21
	v_mul_f32_e32 v29, 0x4f800000, v21
	v_cmp_gt_f32_e32 vcc, s53, v21
	s_nop 1
	v_cndmask_b32_e32 v21, v21, v29, vcc
	v_sqrt_f32_e32 v29, v21
	s_nop 0
	v_add_u32_e32 v104, -1, v29
	v_add_u32_e32 v105, 1, v29
	v_fma_f32 v106, -v104, v29, v21
	v_fma_f32 v107, -v105, v29, v21
	v_cmp_ge_f32_e64 s[10:11], 0, v106
	s_nop 1
	v_cndmask_b32_e64 v29, v29, v104, s[10:11]
	v_cmp_lt_f32_e64 s[10:11], 0, v107
	s_nop 1
	v_cndmask_b32_e64 v29, v29, v105, s[10:11]
	v_mul_f32_e32 v104, 0x37800000, v29
	v_cndmask_b32_e32 v29, v29, v104, vcc
	v_cmp_class_f32_e32 vcc, v21, v195
	s_nop 1
	v_cndmask_b32_e32 v21, v29, v21, vcc
	v_div_scale_f32 v29, s[10:11], v21, v21, 1.0
	v_rcp_f32_e32 v104, v29
	s_nop 0
	v_fma_f32 v105, -v29, v104, 1.0
	v_fmac_f32_e32 v104, v105, v104
	v_div_scale_f32 v105, vcc, 1.0, v21, 1.0
	v_mul_f32_e32 v106, v105, v104
	v_fma_f32 v107, -v29, v106, v105
	v_fmac_f32_e32 v106, v107, v104
	v_fma_f32 v29, -v29, v106, v105
	v_div_fmas_f32 v29, v29, v104, v106
	v_div_fixup_f32 v104, v29, v21, 1.0
	v_pk_mul_f32 v[96:97], v[96:97], v[104:105] op_sel_hi:[1,0]
	v_pk_mul_f32 v[98:99], v[98:99], v[104:105] op_sel_hi:[1,0]
	v_pk_mul_f32 v[100:101], v[100:101], v[104:105] op_sel_hi:[1,0]
	v_pk_mul_f32 v[102:103], v[102:103], v[104:105] op_sel_hi:[1,0]
; __device__ __forceinline__ unsigned pk2(float lo, float hi) { unsigned r; asm("v_cvt_pk_bf16_f32 %0, %1, %2" : "=v"(r) : "v"(lo), "v"(hi)); return r; }
; __device__ __forceinline__ float siluf(float v) { return v * __builtin_amdgcn_rcpf(1.f + __expf(-v)); }
; __device__ __forceinline__ void dn_conv_token4(const P& p, int m0, int lane) {
;     ...
;         bf16_t* dbase = (bf16_t*)(p.ws + (cgp == 0 ? WS_QN : (cgp == 1 ? WS_KN : WS_VV))) + lane * 8;
; #pragma unroll
;         for (int t = 0; t < 4; ++t) {
;             float acc[8];
; #pragma unroll
;             for (int i = 0; i < 8; ++i) acc[i] = 0.f;
; #pragma unroll
;             for (int j = 0; j < 5; ++j) { const u32x4 xv = xr[t + j];
;                 acc[0] += bflo(xv.x) * w[j][0][0]; acc[1] += bfhi(xv.x) * w[j][0][1]; acc[2] += bflo(xv.y) * w[j][0][2]; acc[3] += bfhi(xv.y) * w[j][0][3];
;                 acc[4] += bflo(xv.z) * w[j][1][0]; acc[5] += bfhi(xv.z) * w[j][1][1]; acc[6] += bflo(xv.w) * w[j][1][2]; acc[7] += bfhi(xv.w) * w[j][1][3]; }
;             float ss = 0.f;
; #pragma unroll
;             for (int i = 0; i < 8; ++i) { acc[i] = siluf(acc[i]); ss += acc[i] * acc[i]; }
;             if (cgp < 2) {
;                 ss += __shfl_xor(ss, 1); ss += __shfl_xor(ss, 2); ss += __shfl_xor(ss, 4); ss += __shfl_xor(ss, 8);
;                 const float rn = 1.0f / sqrtf(ss + EPS);
; #pragma unroll
;                 for (int i = 0; i < 8; ++i) acc[i] *= rn;
;             }
;             u32x4 o; o.x = pk2(acc[0], acc[1]); o.y = pk2(acc[2], acc[3]); o.z = pk2(acc[4], acc[5]); o.w = pk2(acc[6], acc[7]);
;             *(u32x4*)(dbase + (size_t)(m0 + t) * 512) = o;
.LBB0_513:
	v_pk_fma_f32 v[94:95], v[14:15], v[94:95], 0 op_sel_hi:[1,1,0]
	v_cvt_pk_bf16_f32 v105, v96, v97
	v_lshl_add_u64 v[96:97], v[54:55], 0, s[76:77]
	v_pk_fma_f32 v[94:95], v[22:23], v[84:85], v[94:95]
	v_cvt_pk_bf16_f32 v102, v102, v103
	v_cvt_pk_bf16_f32 v103, v100, v101
	v_cvt_pk_bf16_f32 v104, v98, v99
	global_store_dwordx4 v[96:97], v[102:105], off
	v_pk_fma_f32 v[94:95], v[30:31], v[86:87], v[94:95]
	v_lshlrev_b32_e32 v96, 16, v46
	v_and_b32_e32 v97, 0xffff0000, v46
	v_pk_fma_f32 v[94:95], v[34:35], v[72:73], v[94:95]
	v_pk_fma_f32 v[92:93], v[16:17], v[92:93], 0 op_sel_hi:[1,1,0]
	v_pk_fma_f32 v[94:95], v[38:39], v[96:97], v[94:95]
	v_pk_fma_f32 v[92:93], v[24:25], v[66:67], v[92:93]
	v_mul_f32_e32 v29, 0xbfb8aa3b, v94
	v_exp_f32_e32 v29, v29
	v_pk_fma_f32 v[92:93], v[32:33], v[68:69], v[92:93]
	v_pk_mul_f32 v[102:103], v[82:83], v[70:71]
	v_lshlrev_b32_e32 v70, 16, v47
	v_add_f32_e32 v29, 1.0, v29
	v_rcp_f32_e32 v112, v29
	v_mul_f32_e32 v29, 0xbfb8aa3b, v95
	v_exp_f32_e32 v29, v29
	v_and_b32_e32 v71, 0xffff0000, v47
	v_pk_fma_f32 v[92:93], v[36:37], v[56:57], v[92:93]
	v_pk_fma_f32 v[90:91], v[2:3], v[90:91], 0 op_sel_hi:[1,1,0]
	v_add_f32_e32 v29, 1.0, v29
	v_pk_fma_f32 v[92:93], v[40:41], v[70:71], v[92:93]
	v_rcp_f32_e32 v113, v29
	v_mul_f32_e32 v29, 0xbfb8aa3b, v92
	v_exp_f32_e32 v29, v29
	v_pk_fma_f32 v[90:91], v[6:7], v[60:61], v[90:91]
	v_pk_mul_f32 v[94:95], v[94:95], v[112:113]
	v_pk_fma_f32 v[90:91], v[10:11], v[62:63], v[90:91]
	v_add_f32_e32 v29, 1.0, v29
	v_rcp_f32_e32 v112, v29
	v_mul_f32_e32 v29, 0xbfb8aa3b, v93
	v_exp_f32_e32 v29, v29
	v_and_b32_e32 v47, 0xffff0000, v48
	v_lshlrev_b32_e32 v46, 16, v48
	v_pk_fma_f32 v[90:91], v[18:19], v[50:51], v[90:91]
	v_add_f32_e32 v29, 1.0, v29
	v_pk_fma_f32 v[90:91], v[26:27], v[46:47], v[90:91]
	v_rcp_f32_e32 v113, v29
	v_mul_f32_e32 v29, 0xbfb8aa3b, v90
	v_exp_f32_e32 v29, v29
	v_mul_f32_e32 v98, v8, v58
	v_pk_mul_f32 v[92:93], v[92:93], v[112:113]
	v_lshlrev_b32_e32 v21, 16, v49
	v_add_f32_e32 v29, 1.0, v29
	v_rcp_f32_e32 v112, v29
	v_mul_f32_e32 v29, 0xbfb8aa3b, v91
	v_and_b32_e32 v49, 0xffff0000, v49
	v_mov_b32_e32 v48, v53
	v_exp_f32_e32 v29, v29
	v_pk_fma_f32 v[88:89], v[4:5], v[88:89], 0 op_sel_hi:[1,1,0]
	v_mov_b32_e32 v99, v102
	v_mul_f32_e32 v100, v12, v9
	v_pk_mul_f32 v[110:111], v[64:65], v[48:49]
	v_pk_add_f32 v[88:89], v[88:89], v[98:99]
	v_mov_b32_e32 v101, v103
	v_mul_f32_e32 v104, v20, v13
	v_pk_add_f32 v[88:89], v[88:89], v[100:101]
	v_mov_b32_e32 v105, v110
	v_mul_f32_e32 v106, v28, v21
	v_pk_add_f32 v[88:89], v[88:89], v[104:105]
	v_mov_b32_e32 v107, v111
	v_add_f32_e32 v29, 1.0, v29
	v_pk_add_f32 v[88:89], v[88:89], v[106:107]
	v_rcp_f32_e32 v113, v29
	v_mul_f32_e32 v29, 0xbfb8aa3b, v88
	v_exp_f32_e32 v29, v29
	s_and_b64 vcc, exec, s[8:9]
	v_pk_mul_f32 v[90:91], v[90:91], v[112:113]
	v_add_f32_e32 v29, 1.0, v29
	v_rcp_f32_e32 v98, v29
	v_mul_f32_e32 v29, 0xbfb8aa3b, v89
	v_exp_f32_e32 v29, v29
	s_nop 0
	v_add_f32_e32 v29, 1.0, v29
	v_rcp_f32_e32 v99, v29
	s_nop 0
	v_pk_mul_f32 v[88:89], v[88:89], v[98:99]
	s_cbranch_vccnz .LBB0_515
	v_pk_mul_f32 v[98:99], v[94:95], v[94:95]
	v_pk_mul_f32 v[100:101], v[92:93], v[92:93]
	v_add_f32_e32 v29, v98, v99
	v_add_f32_e32 v29, v100, v29
	v_pk_mul_f32 v[102:103], v[90:91], v[90:91]
	v_add_f32_e32 v29, v101, v29
	v_add_f32_e32 v29, v102, v29
	v_pk_mul_f32 v[104:105], v[88:89], v[88:89]
	v_add_f32_e32 v29, v103, v29
	v_cmp_lt_i32_e32 vcc, v192, v186
	v_add_f32_e32 v29, v104, v29
	v_add_f32_e32 v29, v105, v29
	s_nop 1
	v_add_f32_dpp v29, v29, v29 quad_perm:[1,0,3,2] row_mask:0xf bank_mask:0xf
	s_nop 1
	v_add_f32_dpp v29, v29, v29 quad_perm:[2,3,0,1] row_mask:0xf bank_mask:0xf
	s_nop 1
	v_add_f32_dpp v29, v29, v29 row_half_mirror row_mask:0xf bank_mask:0xf
	s_nop 1
	v_add_f32_dpp v29, v29, v29 row_mirror row_mask:0xf bank_mask:0xf
	s_nop 0
	v_add_f32_e32 v29, 0x358637bd, v29
	v_mul_f32_e32 v48, 0x4f800000, v29
	v_cmp_gt_f32_e32 vcc, s53, v29
	s_nop 1
	v_cndmask_b32_e32 v29, v29, v48, vcc
	v_sqrt_f32_e32 v48, v29
	s_nop 0
	v_add_u32_e32 v98, -1, v48
	v_add_u32_e32 v99, 1, v48
	v_fma_f32 v100, -v98, v48, v29
	v_fma_f32 v101, -v99, v48, v29
	v_cmp_ge_f32_e64 s[10:11], 0, v100
	s_nop 1
	v_cndmask_b32_e64 v48, v48, v98, s[10:11]
	v_cmp_lt_f32_e64 s[10:11], 0, v101
	s_nop 1
	v_cndmask_b32_e64 v48, v48, v99, s[10:11]
	v_mul_f32_e32 v98, 0x37800000, v48
	v_cndmask_b32_e32 v48, v48, v98, vcc
	v_cmp_class_f32_e32 vcc, v29, v195
	s_nop 1
	v_cndmask_b32_e32 v29, v48, v29, vcc
	v_div_scale_f32 v48, s[10:11], v29, v29, 1.0
	v_rcp_f32_e32 v98, v48
	s_nop 0
	v_fma_f32 v99, -v48, v98, 1.0
	v_fmac_f32_e32 v98, v99, v98
	v_div_scale_f32 v99, vcc, 1.0, v29, 1.0
	v_mul_f32_e32 v100, v99, v98
	v_fma_f32 v101, -v48, v100, v99
	v_fmac_f32_e32 v100, v101, v98
	v_fma_f32 v48, -v48, v100, v99
	v_div_fmas_f32 v48, v48, v98, v100
	v_div_fixup_f32 v48, v48, v29, 1.0
	v_pk_mul_f32 v[88:89], v[88:89], v[48:49] op_sel_hi:[1,0]
	v_pk_mul_f32 v[90:91], v[90:91], v[48:49] op_sel_hi:[1,0]
	v_pk_mul_f32 v[92:93], v[92:93], v[48:49] op_sel_hi:[1,0]
	v_pk_mul_f32 v[94:95], v[94:95], v[48:49] op_sel_hi:[1,0]
; __device__ __forceinline__ unsigned pk2(float lo, float hi) { unsigned r; asm("v_cvt_pk_bf16_f32 %0, %1, %2" : "=v"(r) : "v"(lo), "v"(hi)); return r; }
; __device__ __forceinline__ float siluf(float v) { return v * __builtin_amdgcn_rcpf(1.f + __expf(-v)); }
; __device__ __forceinline__ void dn_conv_token4(const P& p, int m0, int lane) {
;     ...
;         for (int t = 0; t < 4; ++t) {
;             float acc[8];
; #pragma unroll
;             for (int i = 0; i < 8; ++i) acc[i] = 0.f;
; #pragma unroll
;             for (int j = 0; j < 5; ++j) { const u32x4 xv = xr[t + j];
;                 acc[0] += bflo(xv.x) * w[j][0][0]; acc[1] += bfhi(xv.x) * w[j][0][1]; acc[2] += bflo(xv.y) * w[j][0][2]; acc[3] += bfhi(xv.y) * w[j][0][3];
;                 acc[4] += bflo(xv.z) * w[j][1][0]; acc[5] += bfhi(xv.z) * w[j][1][1]; acc[6] += bflo(xv.w) * w[j][1][2]; acc[7] += bfhi(xv.w) * w[j][1][3]; }
;             float ss = 0.f;
; #pragma unroll
;             for (int i = 0; i < 8; ++i) { acc[i] = siluf(acc[i]); ss += acc[i] * acc[i]; }
;             if (cgp < 2) {
;                 ss += __shfl_xor(ss, 1); ss += __shfl_xor(ss, 2); ss += __shfl_xor(ss, 4); ss += __shfl_xor(ss, 8);
;                 const float rn = 1.0f / sqrtf(ss + EPS);
; #pragma unroll
;                 for (int i = 0; i < 8; ++i) acc[i] *= rn;
;             }
;             u32x4 o; o.x = pk2(acc[0], acc[1]); o.y = pk2(acc[2], acc[3]); o.z = pk2(acc[4], acc[5]); o.w = pk2(acc[6], acc[7]);
;             *(u32x4*)(dbase + (size_t)(m0 + t) * 512) = o;
.LBB0_515:
	v_pk_fma_f32 v[14:15], v[14:15], v[84:85], 0 op_sel_hi:[1,1,0]
	v_mul_f32_e32 v12, v12, v13
	v_pk_fma_f32 v[14:15], v[22:23], v[86:87], v[14:15]
	v_lshlrev_b32_e32 v22, 16, v42
	v_pk_fma_f32 v[14:15], v[30:31], v[72:73], v[14:15]
	v_and_b32_e32 v23, 0xffff0000, v42
	v_pk_fma_f32 v[14:15], v[34:35], v[96:97], v[14:15]
	v_pk_fma_f32 v[16:17], v[16:17], v[66:67], 0 op_sel_hi:[1,1,0]
	v_pk_fma_f32 v[14:15], v[38:39], v[22:23], v[14:15]
	v_pk_fma_f32 v[2:3], v[2:3], v[60:61], 0 op_sel_hi:[1,1,0]
	v_mul_f32_e32 v13, 0xbfb8aa3b, v14
	v_mul_f32_e32 v20, v20, v21
	v_exp_f32_e32 v13, v13
	v_mul_f32_e32 v21, 0xbfb8aa3b, v15
	v_pk_fma_f32 v[16:17], v[24:25], v[68:69], v[16:17]
	v_pk_fma_f32 v[2:3], v[6:7], v[62:63], v[2:3]
	v_exp_f32_e32 v21, v21
	v_pk_fma_f32 v[16:17], v[32:33], v[56:57], v[16:17]
	v_pk_fma_f32 v[2:3], v[10:11], v[50:51], v[2:3]
	v_mul_f32_e32 v48, v8, v9
	v_lshlrev_b32_e32 v8, 16, v45
	v_pk_fma_f32 v[16:17], v[36:37], v[70:71], v[16:17]
	v_lshlrev_b32_e32 v24, 16, v43
	v_and_b32_e32 v25, 0xffff0000, v43
	v_pk_fma_f32 v[2:3], v[18:19], v[46:47], v[2:3]
	v_and_b32_e32 v7, 0xffff0000, v44
	v_lshlrev_b32_e32 v6, 16, v44
	v_mul_f32_e32 v28, v28, v8
	v_and_b32_e32 v9, 0xffff0000, v45
	v_mov_b32_e32 v8, v49
	v_pk_fma_f32 v[16:17], v[40:41], v[24:25], v[16:17]
	v_pk_fma_f32 v[6:7], v[26:27], v[6:7], v[2:3]
	v_pk_mul_f32 v[22:23], v[64:65], v[8:9]
	v_add_f32_e32 v8, 1.0, v13
	v_mul_f32_e32 v13, 0xbfb8aa3b, v16
	v_mul_f32_e32 v2, 0xbfb8aa3b, v6
	v_add_f32_e32 v9, 1.0, v21
	v_exp_f32_e32 v13, v13
	v_mul_f32_e32 v21, 0xbfb8aa3b, v17
	v_exp_f32_e32 v2, v2
	v_mul_f32_e32 v3, 0xbfb8aa3b, v7
	v_rcp_f32_e32 v8, v8
	v_rcp_f32_e32 v9, v9
	v_exp_f32_e32 v21, v21
	v_exp_f32_e32 v3, v3
	v_pk_mul_f32 v[52:53], v[82:83], v[52:53]
	v_add_f32_e32 v13, 1.0, v13
	v_add_f32_e32 v2, 1.0, v2
	v_pk_mul_f32 v[8:9], v[14:15], v[8:9]
	v_rcp_f32_e32 v14, v13
	v_add_f32_e32 v13, 1.0, v21
	v_rcp_f32_e32 v10, v2
	v_add_f32_e32 v11, 1.0, v3
	v_pk_fma_f32 v[2:3], v[4:5], v[58:59], 0 op_sel_hi:[1,1,0]
	v_mov_b32_e32 v49, v52
	v_rcp_f32_e32 v15, v13
	v_pk_add_f32 v[2:3], v[2:3], v[48:49]
	v_mov_b32_e32 v13, v53
	v_pk_add_f32 v[2:3], v[2:3], v[12:13]
	v_mov_b32_e32 v21, v22
	v_pk_add_f32 v[2:3], v[2:3], v[20:21]
	v_mov_b32_e32 v29, v23
	v_pk_add_f32 v[12:13], v[2:3], v[28:29]
	v_rcp_f32_e32 v11, v11
	v_mul_f32_e32 v2, 0xbfb8aa3b, v12
	v_exp_f32_e32 v2, v2
	v_mul_f32_e32 v3, 0xbfb8aa3b, v13
	v_exp_f32_e32 v3, v3
	v_cvt_pk_bf16_f32 v101, v88, v89
	v_add_f32_e32 v2, 1.0, v2
	v_rcp_f32_e32 v18, v2
	v_add_f32_e32 v2, 1.0, v3
	v_rcp_f32_e32 v19, v2
	v_lshl_add_u64 v[88:89], v[54:55], 0, s[80:81]
	v_pk_mul_f32 v[2:3], v[16:17], v[14:15]
	v_pk_mul_f32 v[4:5], v[6:7], v[10:11]
	s_and_b64 vcc, exec, s[8:9]
	v_pk_mul_f32 v[6:7], v[12:13], v[18:19]
	v_cvt_pk_bf16_f32 v98, v94, v95
	v_cvt_pk_bf16_f32 v99, v92, v93
	v_cvt_pk_bf16_f32 v100, v90, v91
	global_store_dwordx4 v[88:89], v[98:101], off
	s_cbranch_vccnz .LBB0_492
	v_pk_mul_f32 v[10:11], v[8:9], v[8:9]
	v_pk_mul_f32 v[12:13], v[2:3], v[2:3]
	v_add_f32_e32 v10, v10, v11
	v_add_f32_e32 v10, v12, v10
	v_pk_mul_f32 v[14:15], v[4:5], v[4:5]
	v_add_f32_e32 v10, v13, v10
	v_add_f32_e32 v10, v14, v10
	v_pk_mul_f32 v[16:17], v[6:7], v[6:7]
	v_add_f32_e32 v10, v15, v10
	v_cmp_lt_i32_e32 vcc, v192, v186
	v_add_f32_e32 v10, v16, v10
	v_add_f32_e32 v10, v17, v10
	s_nop 1
	v_add_f32_dpp v10, v10, v10 quad_perm:[1,0,3,2] row_mask:0xf bank_mask:0xf
	s_nop 1
	v_add_f32_dpp v10, v10, v10 quad_perm:[2,3,0,1] row_mask:0xf bank_mask:0xf
	s_nop 1
	v_add_f32_dpp v10, v10, v10 row_half_mirror row_mask:0xf bank_mask:0xf
	s_nop 1
	v_add_f32_dpp v10, v10, v10 row_mirror row_mask:0xf bank_mask:0xf
	s_nop 0
	v_add_f32_e32 v10, 0x358637bd, v10
	v_mul_f32_e32 v11, 0x4f800000, v10
	v_cmp_gt_f32_e32 vcc, s53, v10
	s_nop 1
	v_cndmask_b32_e32 v10, v10, v11, vcc
	v_sqrt_f32_e32 v11, v10
	s_nop 0
	v_add_u32_e32 v12, -1, v11
	v_add_u32_e32 v13, 1, v11
	v_fma_f32 v14, -v12, v11, v10
	v_fma_f32 v15, -v13, v11, v10
	v_cmp_ge_f32_e64 s[8:9], 0, v14
	s_nop 1
	v_cndmask_b32_e64 v11, v11, v12, s[8:9]
	v_cmp_lt_f32_e64 s[8:9], 0, v15
	s_nop 1
	v_cndmask_b32_e64 v11, v11, v13, s[8:9]
	v_mul_f32_e32 v12, 0x37800000, v11
	v_cndmask_b32_e32 v11, v11, v12, vcc
	v_cmp_class_f32_e32 vcc, v10, v195
	s_nop 1
	v_cndmask_b32_e32 v10, v11, v10, vcc
	v_div_scale_f32 v11, s[8:9], v10, v10, 1.0
	v_rcp_f32_e32 v12, v11
	s_nop 0
	v_fma_f32 v13, -v11, v12, 1.0
	v_fmac_f32_e32 v12, v13, v12
	v_div_scale_f32 v13, vcc, 1.0, v10, 1.0
	v_mul_f32_e32 v14, v13, v12
	v_fma_f32 v15, -v11, v14, v13
	v_fmac_f32_e32 v14, v15, v12
	v_fma_f32 v11, -v11, v14, v13
	v_div_fmas_f32 v11, v11, v12, v14
	v_div_fixup_f32 v10, v11, v10, 1.0
	v_pk_mul_f32 v[6:7], v[6:7], v[10:11] op_sel_hi:[1,0]
	v_pk_mul_f32 v[4:5], v[4:5], v[10:11] op_sel_hi:[1,0]
	v_pk_mul_f32 v[2:3], v[2:3], v[10:11] op_sel_hi:[1,0]
	v_pk_mul_f32 v[8:9], v[8:9], v[10:11] op_sel_hi:[1,0]
	s_branch .LBB0_492
